# hyena staging/epilogue loads issued together, hyena loop pipelined; odd_prep boundary-row loads no longer drain the queue
# speedup vs baseline: 1.0041x; 1.0041x over previous
.LBB0_524:
	s_and_b64 vcc, exec, s[14:15]
	s_cbranch_vccz .LBB0_498
	s_lshl_b32 s10, s6, 3
	s_and_b32 s11, s10, 0x1f8
	s_cmp_gt_i32 s6, 63
	s_cselect_b64 s[40:41], -1, 0
	v_mov_b32_e32 v34, v202
	s_and_b64 s[4:5], s[40:41], exec
	s_load_dwordx2 s[42:43], s[8:9], 0xc0
	s_cselect_b32 s38, s11, s10
	v_ashrrev_i32_e32 v35, 6, v34
	s_movk_i32 s4, 0x400
	v_add_u32_e32 v2, s38, v35
	v_and_b32_e32 v8, 63, v34
	s_cselect_b32 s7, 0x100, s4
	v_ashrrev_i32_e32 v3, 31, v2
	s_cselect_b32 s4, 9, 11
	v_lshlrev_b64 v[6:7], s4, v[2:3]
	s_cselect_b32 s4, 0, 0x80000
	v_lshlrev_b32_e32 v4, 4, v8
	v_lshlrev_b32_e32 v5, 12, v35
	v_or_b32_e32 v0, s4, v4
	v_or_b32_e32 v3, v5, v4
	s_add_i32 s5, 0, 0x8000
	v_lshl_add_u64 v[6:7], v[6:7], 1, v[0:1]
	s_lshr_b32 s10, s7, 2
	v_add_u32_e32 v9, s5, v3
	v_lshl_add_u64 v[6:7], s[24:25], 0, v[6:7]
	s_mov_b64 s[14:15], 0
	v_mov_b32_e32 v0, v8
	global_load_dwordx4 v[56:59], v[6:7], off
	s_cmp_eq_u32 s10, 64
	s_cbranch_scc1 .Lhy_gr_short
	global_load_dwordx4 v[60:63], v[6:7], off offset:1024
	global_load_dwordx4 v[64:67], v[6:7], off offset:2048
	global_load_dwordx4 v[68:71], v[6:7], off offset:3072
.Lhy_gr_short:
	s_lshl_b32 s4, s6, 5
	s_and_b32 s4, s4, 0xfffff800
	s_add_i32 s6, s4, 0xfffff800
	s_and_b64 s[4:5], s[40:41], exec
	s_cselect_b32 s44, s6, 0x1000
	v_mad_i64_i32 v[10:11], s[4:5], v2, s68, 0
	s_ashr_i32 s45, s44, 31
	s_add_i32 s4, 0, 0x10000
	v_add_u32_e32 v6, s4, v3
	s_lshl_b64 s[4:5], s[44:45], 1
	v_readlane_b32 s10, v254, 47
	v_readlane_b32 s11, v254, 48
	s_add_u32 s4, s10, s4
	v_or_b32_e32 v10, v10, v4
	s_addc_u32 s5, s11, s5
	v_lshl_add_u64 v[2:3], s[4:5], 0, v[10:11]
	global_load_dwordx4 v[72:75], v[2:3], off
	global_load_dwordx4 v[76:79], v[2:3], off offset:1024
	global_load_dwordx4 v[80:83], v[2:3], off offset:2048
	global_load_dwordx4 v[84:87], v[2:3], off offset:3072
	s_waitcnt vmcnt(4)
	ds_write_b128 v9, v[56:59]
	s_and_b64 vcc, exec, s[40:41]
	s_cbranch_vccnz .Lhy_gw_short
	ds_write_b128 v9, v[60:63] offset:1024
	ds_write_b128 v9, v[64:67] offset:2048
	ds_write_b128 v9, v[68:71] offset:3072
.Lhy_gw_short:
	s_waitcnt vmcnt(0)
	ds_write_b128 v6, v[72:75]
	ds_write_b128 v6, v[76:79] offset:1024
	ds_write_b128 v6, v[80:83] offset:2048
	ds_write_b128 v6, v[84:87] offset:3072
	s_or_b64 exec, exec, s[14:15]
	v_cmp_gt_i32_e32 vcc, 8, v34
	s_and_saveexec_b64 s[14:15], vcc
	v_lshl_add_u32 v0, v34, 2, 0
	v_add_u32_e32 v0, 0x18000, v0
	ds_write_b32 v0, v1
	s_or_b64 exec, exec, s[14:15]
	s_lshr_b32 s6, s7, 5
	s_and_b64 s[4:5], s[40:41], exec
	s_cselect_b32 s10, 3, 5
	s_add_i32 s11, s6, -1
	v_and_b32_e32 v2, 31, v34
	s_and_b64 s[4:5], s[40:41], exec
	s_cselect_b32 s4, 8, 10
	v_lshrrev_b32_e32 v0, s10, v2
	v_lshlrev_b32_e32 v38, s4, v0
	v_or_b32_e32 v0, 32, v2
	v_lshl_add_u32 v3, s7, 2, v5
	v_lshlrev_b32_e32 v2, 1, v2
	v_bitop3_b32 v37, v34, s11, 31 bitop3:0x80
	v_lshrrev_b32_e32 v0, s10, v0
	v_sub_u32_e32 v2, v3, v2
	v_readlane_b32 s5, v253, 18
	v_lshlrev_b32_e32 v0, s4, v0
	v_lshlrev_b32_e32 v4, 1, v0
	v_add_u32_e32 v40, s5, v2
	v_add_u32_e32 v2, s6, v37
	v_lshl_add_u32 v3, v2, 6, v5
	v_lshrrev_b32_e32 v36, 5, v8
	s_lshr_b32 s4, s7, 4
	v_add3_u32 v41, v3, v4, 0
	v_lshlrev_b32_e32 v4, 1, v38
	v_mov_b32_e32 v18, 0
	v_lshlrev_b32_e32 v39, 4, v36
	s_add_i32 s7, s4, -1
	v_add3_u32 v42, v3, v4, 0
	v_add_u32_e32 v43, -1, v2
	v_mov_b32_e32 v19, v18
	v_mov_b32_e32 v20, v18
	v_mov_b32_e32 v21, v18
	v_mov_b32_e32 v22, v18
	v_mov_b32_e32 v23, v18
	v_mov_b32_e32 v24, v18
	v_mov_b32_e32 v25, v18
	v_mov_b32_e32 v26, v18
	v_mov_b32_e32 v27, v18
	v_mov_b32_e32 v28, v18
	v_mov_b32_e32 v29, v18
	v_mov_b32_e32 v30, v18
	v_mov_b32_e32 v31, v18
	v_mov_b32_e32 v32, v18
	v_mov_b32_e32 v33, v18
	v_mov_b32_e32 v2, v18
	v_mov_b32_e32 v3, v18
	v_mov_b32_e32 v4, v18
	v_mov_b32_e32 v5, v18
	v_mov_b32_e32 v6, v18
	v_mov_b32_e32 v7, v18
	v_mov_b32_e32 v8, v18
	v_mov_b32_e32 v9, v18
	v_mov_b32_e32 v10, v18
	v_mov_b32_e32 v11, v18
	v_mov_b32_e32 v12, v18
	v_mov_b32_e32 v13, v18
	v_mov_b32_e32 v14, v18
	v_mov_b32_e32 v15, v18
	v_mov_b32_e32 v16, v18
	v_mov_b32_e32 v17, v18
	s_waitcnt lgkmcnt(0)
	s_barrier
	s_add_i32 s4, 0, 0x18000
	v_mov_b32_e32 v54, s4
	v_add_u32_e32 v52, v40, v39
	ds_read_u16 v104, v52
	ds_read_u16 v105, v52 offset:2
	ds_read_u16 v106, v52 offset:4
	ds_read_u16 v107, v52 offset:6
	ds_read_u16 v108, v52 offset:8
	ds_read_u16 v109, v52 offset:10
	ds_read_u16 v110, v52 offset:12
	ds_read_u16 v111, v52 offset:14
	v_cmp_lt_i32_e32 vcc, -1, v43
	v_cmp_gt_i32_e64 s[40:41], s6, v43
	v_add_u32_e32 v53, v42, v39
	v_add_u32_e32 v55, v41, v39
	s_and_b64 vcc, vcc, s[40:41]
	v_add_u32_e32 v120, 0xffc0, v53
	v_add_u32_e32 v121, 0xffc0, v55
	v_add_u32_e32 v122, 0xffe0, v53
	v_add_u32_e32 v123, 0xffe0, v55
	v_cndmask_b32_e32 v120, v54, v120, vcc
	v_cndmask_b32_e32 v121, v54, v121, vcc
	v_cndmask_b32_e32 v122, v54, v122, vcc
	v_cndmask_b32_e32 v123, v54, v123, vcc
	ds_read_b128 v[48:51], v120
	ds_read_b128 v[92:95], v121
	ds_read_b128 v[96:99], v122
	ds_read_b128 v[100:103], v123
	s_waitcnt lgkmcnt(7)
	ds_read_u16 v112, v52 offset:32
	ds_read_u16 v113, v52 offset:34
	ds_read_u16 v114, v52 offset:36
	ds_read_u16 v115, v52 offset:38
	ds_read_u16 v116, v52 offset:40
	ds_read_u16 v117, v52 offset:42
	ds_read_u16 v118, v52 offset:44
	ds_read_u16 v119, v52 offset:46
	v_subrev_u32_e32 v40, 64, v40
	v_subrev_u32_e32 v41, 64, v41
	v_subrev_u32_e32 v42, 64, v42
	v_add_u32_e32 v43, -1, v43
	s_waitcnt lgkmcnt(0)
	v_perm_b32 v44, v105, v104, s86
	v_perm_b32 v45, v107, v106, s86
	v_perm_b32 v46, v109, v108, s86
	v_perm_b32 v47, v111, v110, s86
	v_perm_b32 v88, v113, v112, s86
	v_perm_b32 v89, v115, v114, s86
	v_perm_b32 v90, v117, v116, s86
	v_perm_b32 v91, v119, v118, s86
.LBB0_532:
	v_mfma_f32_32x32x16_bf16 v[18:33], v[44:47], v[48:51], v[18:33]
	v_mfma_f32_32x32x16_bf16 v[2:17], v[44:47], v[92:95], v[2:17]
	v_mfma_f32_32x32x16_bf16 v[18:33], v[88:91], v[96:99], v[18:33]
	v_mfma_f32_32x32x16_bf16 v[2:17], v[88:91], v[100:103], v[2:17]
	s_add_i32 s7, s7, -1
	v_add_u32_e32 v52, v40, v39
	ds_read_u16 v104, v52
	ds_read_u16 v105, v52 offset:2
	ds_read_u16 v106, v52 offset:4
	ds_read_u16 v107, v52 offset:6
	ds_read_u16 v108, v52 offset:8
	ds_read_u16 v109, v52 offset:10
	ds_read_u16 v110, v52 offset:12
	ds_read_u16 v111, v52 offset:14
	v_cmp_lt_i32_e32 vcc, -1, v43
	v_cmp_gt_i32_e64 s[40:41], s6, v43
	v_add_u32_e32 v53, v42, v39
	v_add_u32_e32 v55, v41, v39
	s_and_b64 vcc, vcc, s[40:41]
	v_add_u32_e32 v120, 0xffc0, v53
	v_add_u32_e32 v121, 0xffc0, v55
	v_add_u32_e32 v122, 0xffe0, v53
	v_add_u32_e32 v123, 0xffe0, v55
	v_cndmask_b32_e32 v120, v54, v120, vcc
	v_cndmask_b32_e32 v121, v54, v121, vcc
	v_cndmask_b32_e32 v122, v54, v122, vcc
	v_cndmask_b32_e32 v123, v54, v123, vcc
	ds_read_b128 v[48:51], v120
	ds_read_b128 v[92:95], v121
	ds_read_b128 v[96:99], v122
	ds_read_b128 v[100:103], v123
	s_waitcnt lgkmcnt(7)
	ds_read_u16 v112, v52 offset:32
	ds_read_u16 v113, v52 offset:34
	ds_read_u16 v114, v52 offset:36
	ds_read_u16 v115, v52 offset:38
	ds_read_u16 v116, v52 offset:40
	ds_read_u16 v117, v52 offset:42
	ds_read_u16 v118, v52 offset:44
	ds_read_u16 v119, v52 offset:46
	v_subrev_u32_e32 v40, 64, v40
	v_subrev_u32_e32 v41, 64, v41
	v_subrev_u32_e32 v42, 64, v42
	v_add_u32_e32 v43, -1, v43
	s_waitcnt lgkmcnt(0)
	v_perm_b32 v44, v105, v104, s86
	v_perm_b32 v45, v107, v106, s86
	v_perm_b32 v46, v109, v108, s86
	v_perm_b32 v47, v111, v110, s86
	v_perm_b32 v88, v113, v112, s86
	v_perm_b32 v89, v115, v114, s86
	v_perm_b32 v90, v117, v116, s86
	v_perm_b32 v91, v119, v118, s86
	s_cmp_lg_u32 s7, 0
	s_cbranch_scc1 .LBB0_532
	v_lshlrev_b32_e32 v37, 5, v37
	v_lshlrev_b32_e32 v36, 2, v36
	v_add_u32_e32 v38, v38, v37
	v_lshl_add_u32 v35, v35, 1, 0
	v_or_b32_e32 v38, v38, v36
	v_bfe_u32 v39, v18, 16, 1
	v_add3_u32 v18, v18, v39, s27
	v_lshl_add_u32 v38, v38, 4, v35
	ds_write_b16_d16_hi v38, v18
	v_bfe_u32 v18, v19, 16, 1
	v_add3_u32 v18, v19, v18, s27
	ds_write_b16_d16_hi v38, v18 offset:16
	v_bfe_u32 v18, v20, 16, 1
	v_add3_u32 v18, v20, v18, s27
	ds_write_b16_d16_hi v38, v18 offset:32
	v_bfe_u32 v18, v21, 16, 1
	v_add3_u32 v18, v21, v18, s27
	ds_write_b16_d16_hi v38, v18 offset:48
	v_bfe_u32 v18, v22, 16, 1
	v_add3_u32 v18, v22, v18, s27
	ds_write_b16_d16_hi v38, v18 offset:128
	v_bfe_u32 v18, v23, 16, 1
	v_add3_u32 v18, v23, v18, s27
	ds_write_b16_d16_hi v38, v18 offset:144
	v_bfe_u32 v18, v24, 16, 1
	v_add3_u32 v18, v24, v18, s27
	ds_write_b16_d16_hi v38, v18 offset:160
	v_bfe_u32 v18, v25, 16, 1
	v_add3_u32 v18, v25, v18, s27
	ds_write_b16_d16_hi v38, v18 offset:176
	v_bfe_u32 v18, v26, 16, 1
	v_add3_u32 v18, v26, v18, s27
	ds_write_b16_d16_hi v38, v18 offset:256
	v_bfe_u32 v18, v27, 16, 1
	v_add3_u32 v18, v27, v18, s27
	ds_write_b16_d16_hi v38, v18 offset:272
	v_bfe_u32 v18, v28, 16, 1
	v_add3_u32 v18, v28, v18, s27
	ds_write_b16_d16_hi v38, v18 offset:288
	v_bfe_u32 v18, v29, 16, 1
	v_add3_u32 v18, v29, v18, s27
	ds_write_b16_d16_hi v38, v18 offset:304
	v_bfe_u32 v18, v30, 16, 1
	v_add3_u32 v18, v30, v18, s27
	ds_write_b16_d16_hi v38, v18 offset:384
	v_bfe_u32 v18, v31, 16, 1
	v_add3_u32 v18, v31, v18, s27
	ds_write_b16_d16_hi v38, v18 offset:400
	v_bfe_u32 v18, v32, 16, 1
	v_add3_u32 v18, v32, v18, s27
	ds_write_b16_d16_hi v38, v18 offset:416
	v_bfe_u32 v18, v33, 16, 1
	v_add3_u32 v18, v33, v18, s27
	v_add_u32_e32 v0, v0, v37
	ds_write_b16_d16_hi v38, v18 offset:432
	v_or_b32_e32 v0, v0, v36
	v_bfe_u32 v18, v2, 16, 1
	v_add3_u32 v2, v2, v18, s27
	v_lshl_add_u32 v0, v0, 4, v35
	ds_write_b16_d16_hi v0, v2
	v_bfe_u32 v2, v3, 16, 1
	v_add3_u32 v2, v3, v2, s27
	ds_write_b16_d16_hi v0, v2 offset:16
	v_bfe_u32 v2, v4, 16, 1
	v_add3_u32 v2, v4, v2, s27
	ds_write_b16_d16_hi v0, v2 offset:32
	v_bfe_u32 v2, v5, 16, 1
	v_add3_u32 v2, v5, v2, s27
	ds_write_b16_d16_hi v0, v2 offset:48
	v_bfe_u32 v2, v6, 16, 1
	v_add3_u32 v2, v6, v2, s27
	ds_write_b16_d16_hi v0, v2 offset:128
	v_bfe_u32 v2, v7, 16, 1
	v_add3_u32 v2, v7, v2, s27
	ds_write_b16_d16_hi v0, v2 offset:144
	v_bfe_u32 v2, v8, 16, 1
	v_add3_u32 v2, v8, v2, s27
	ds_write_b16_d16_hi v0, v2 offset:160
	v_bfe_u32 v2, v9, 16, 1
	v_add3_u32 v2, v9, v2, s27
	ds_write_b16_d16_hi v0, v2 offset:176
	v_bfe_u32 v2, v10, 16, 1
	v_add3_u32 v2, v10, v2, s27
	ds_write_b16_d16_hi v0, v2 offset:256
	v_bfe_u32 v2, v11, 16, 1
	v_add3_u32 v2, v11, v2, s27
	ds_write_b16_d16_hi v0, v2 offset:272
	v_bfe_u32 v2, v12, 16, 1
	v_add3_u32 v2, v12, v2, s27
	ds_write_b16_d16_hi v0, v2 offset:288
	v_bfe_u32 v2, v13, 16, 1
	v_add3_u32 v2, v13, v2, s27
	ds_write_b16_d16_hi v0, v2 offset:304
	v_bfe_u32 v2, v14, 16, 1
	v_add3_u32 v2, v14, v2, s27
	ds_write_b16_d16_hi v0, v2 offset:384
	v_bfe_u32 v2, v15, 16, 1
	v_add3_u32 v2, v15, v2, s27
	ds_write_b16_d16_hi v0, v2 offset:400
	v_bfe_u32 v2, v16, 16, 1
	v_add3_u32 v2, v16, v2, s27
	ds_write_b16_d16_hi v0, v2 offset:416
	v_bfe_u32 v2, v17, 16, 1
	s_movk_i32 s4, 0x800
	v_add3_u32 v2, v17, v2, s27
	v_cmp_gt_i32_e32 vcc, s4, v34
	ds_write_b16_d16_hi v0, v2 offset:432
	s_waitcnt lgkmcnt(0)
	s_barrier
	s_and_saveexec_b64 s[40:41], vcc
	s_mov_b64 s[10:11], 0x100000
	s_cbranch_execz .LBB0_497
	s_add_i32 s4, s38, s3
	s_ashr_i32 s5, s4, 31
	s_lshl_b64 s[4:5], s[4:5], 2
	s_add_u32 s4, s42, s4
	s_addc_u32 s5, s43, s5
	global_load_dwordx4 v[2:5], v1, s[4:5] offset:16
	global_load_dwordx4 v[6:9], v1, s[4:5]
	s_ashr_i32 s39, s38, 31
	v_add_u32_e32 v12, s44, v34
	s_lshl_b64 s[4:5], s[38:39], 1
	v_readlane_b32 s6, v253, 50
	v_ashrrev_i32_e32 v13, 31, v12
	v_readlane_b32 s7, v253, 51
	s_add_u32 s6, s6, s4
	v_lshlrev_b64 v[10:11], 11, v[12:13]
	s_addc_u32 s7, s7, s5
	v_lshl_add_u64 v[10:11], s[6:7], 0, v[10:11]
	v_readlane_b32 s6, v254, 49
	v_readlane_b32 s7, v254, 50
	s_add_u32 s4, s6, s4
	v_lshlrev_b64 v[12:13], 10, v[12:13]
	s_addc_u32 s5, s7, s5
	v_add_u32_e32 v0, 0xfffffe00, v34
	v_lshl_add_u32 v14, v34, 4, 0
	v_lshl_add_u64 v[12:13], s[4:5], 0, v[12:13]
	s_mov_b64 s[38:39], 0
	s_mov_b64 s[4:5], 0x80000
	global_load_dwordx4 v[56:59], v[12:13], off
	v_add_co_u32_e32 v24, vcc, 0x600000, v12
	s_nop 1
	v_addc_co_u32_e32 v25, vcc, 0, v13, vcc
	global_load_dwordx4 v[72:75], v[24:25], off
	ds_read_b128 v[88:91], v14
	v_lshl_add_u64 v[12:13], v[12:13], 0, s[4:5]
	global_load_dwordx4 v[60:63], v[12:13], off
	v_add_co_u32_e32 v24, vcc, 0x600000, v12
	s_nop 1
	v_addc_co_u32_e32 v25, vcc, 0, v13, vcc
	global_load_dwordx4 v[76:79], v[24:25], off
	ds_read_b128 v[92:95], v14 offset:8192
	v_lshl_add_u64 v[12:13], v[12:13], 0, s[4:5]
	global_load_dwordx4 v[64:67], v[12:13], off
	v_add_co_u32_e32 v24, vcc, 0x600000, v12
	s_nop 1
	v_addc_co_u32_e32 v25, vcc, 0, v13, vcc
	global_load_dwordx4 v[80:83], v[24:25], off
	ds_read_b128 v[96:99], v14 offset:16384
	v_lshl_add_u64 v[12:13], v[12:13], 0, s[4:5]
	global_load_dwordx4 v[68:71], v[12:13], off
	v_add_co_u32_e32 v24, vcc, 0x600000, v12
	s_nop 1
	v_addc_co_u32_e32 v25, vcc, 0, v13, vcc
	global_load_dwordx4 v[84:87], v[24:25], off
	ds_read_b128 v[100:103], v14 offset:24576
	v_lshl_add_u64 v[12:13], v[12:13], 0, s[4:5]
	s_waitcnt vmcnt(6) lgkmcnt(3)
	v_mov_b32_e32 v16, v88
	v_mov_b32_e32 v17, v89
	v_mov_b32_e32 v18, v90
	v_mov_b32_e32 v19, v91
	v_mov_b32_e32 v20, v56
	v_mov_b32_e32 v21, v57
	v_mov_b32_e32 v22, v58
	v_mov_b32_e32 v23, v59
	v_mov_b32_e32 v24, v72
	v_mov_b32_e32 v25, v73
	v_mov_b32_e32 v26, v74
	v_mov_b32_e32 v27, v75
	v_and_b32_e32 v31, 0xffff0000, v16
	v_lshlrev_b32_e32 v30, 16, v16
	v_and_b32_e32 v29, 0xffff0000, v20
	v_lshlrev_b32_e32 v28, 16, v20
	v_lshlrev_b32_e32 v20, 16, v17
	v_and_b32_e32 v33, 0xffff0000, v24
	v_lshlrev_b32_e32 v32, 16, v24
	v_pk_fma_f32 v[30:31], v[6:7], v[32:33], v[30:31]
	v_lshlrev_b32_e32 v16, 16, v25
	v_pk_mul_f32 v[28:29], v[30:31], v[28:29]
	v_and_b32_e32 v31, 0xffff0000, v21
	v_lshlrev_b32_e32 v30, 16, v21
	v_and_b32_e32 v21, 0xffff0000, v17
	v_and_b32_e32 v17, 0xffff0000, v25
	v_pk_fma_f32 v[16:17], v[8:9], v[16:17], v[20:21]
	v_and_b32_e32 v25, 0xffff0000, v18
	v_pk_mul_f32 v[20:21], v[16:17], v[30:31]
	v_lshlrev_b32_e32 v24, 16, v18
	v_and_b32_e32 v31, 0xffff0000, v26
	v_lshlrev_b32_e32 v30, 16, v26
	v_and_b32_e32 v17, 0xffff0000, v22
	v_lshlrev_b32_e32 v16, 16, v22
	v_pk_fma_f32 v[24:25], v[2:3], v[30:31], v[24:25]
	v_lshlrev_b32_e32 v22, 16, v19
	v_pk_mul_f32 v[24:25], v[24:25], v[16:17]
	v_and_b32_e32 v17, 0xffff0000, v23
	v_lshlrev_b32_e32 v16, 16, v23
	v_and_b32_e32 v23, 0xffff0000, v19
	v_and_b32_e32 v19, 0xffff0000, v27
	v_lshlrev_b32_e32 v18, 16, v27
	v_pk_fma_f32 v[18:19], v[4:5], v[18:19], v[22:23]
	s_nop 0
	v_pk_mul_f32 v[22:23], v[18:19], v[16:17]
	v_cvt_pk_bf16_f32 v16, v28, v29
	v_cvt_pk_bf16_f32 v17, v20, v21
	v_cvt_pk_bf16_f32 v18, v24, v25
	v_cvt_pk_bf16_f32 v19, v22, v23
	global_store_dwordx4 v[10:11], v[16:19], off
	v_lshl_add_u64 v[10:11], v[10:11], 0, s[10:11]
	s_nop 1
	s_waitcnt vmcnt(5) lgkmcnt(2)
	v_mov_b32_e32 v16, v92
	v_mov_b32_e32 v17, v93
	v_mov_b32_e32 v18, v94
	v_mov_b32_e32 v19, v95
	v_mov_b32_e32 v20, v60
	v_mov_b32_e32 v21, v61
	v_mov_b32_e32 v22, v62
	v_mov_b32_e32 v23, v63
	v_mov_b32_e32 v24, v76
	v_mov_b32_e32 v25, v77
	v_mov_b32_e32 v26, v78
	v_mov_b32_e32 v27, v79
	v_and_b32_e32 v31, 0xffff0000, v16
	v_lshlrev_b32_e32 v30, 16, v16
	v_and_b32_e32 v29, 0xffff0000, v20
	v_lshlrev_b32_e32 v28, 16, v20
	v_lshlrev_b32_e32 v20, 16, v17
	v_and_b32_e32 v33, 0xffff0000, v24
	v_lshlrev_b32_e32 v32, 16, v24
	v_pk_fma_f32 v[30:31], v[6:7], v[32:33], v[30:31]
	v_lshlrev_b32_e32 v16, 16, v25
	v_pk_mul_f32 v[28:29], v[30:31], v[28:29]
	v_and_b32_e32 v31, 0xffff0000, v21
	v_lshlrev_b32_e32 v30, 16, v21
	v_and_b32_e32 v21, 0xffff0000, v17
	v_and_b32_e32 v17, 0xffff0000, v25
	v_pk_fma_f32 v[16:17], v[8:9], v[16:17], v[20:21]
	v_and_b32_e32 v25, 0xffff0000, v18
	v_pk_mul_f32 v[20:21], v[16:17], v[30:31]
	v_lshlrev_b32_e32 v24, 16, v18
	v_and_b32_e32 v31, 0xffff0000, v26
	v_lshlrev_b32_e32 v30, 16, v26
	v_and_b32_e32 v17, 0xffff0000, v22
	v_lshlrev_b32_e32 v16, 16, v22
	v_pk_fma_f32 v[24:25], v[2:3], v[30:31], v[24:25]
	v_lshlrev_b32_e32 v22, 16, v19
	v_pk_mul_f32 v[24:25], v[24:25], v[16:17]
	v_and_b32_e32 v17, 0xffff0000, v23
	v_lshlrev_b32_e32 v16, 16, v23
	v_and_b32_e32 v23, 0xffff0000, v19
	v_and_b32_e32 v19, 0xffff0000, v27
	v_lshlrev_b32_e32 v18, 16, v27
	v_pk_fma_f32 v[18:19], v[4:5], v[18:19], v[22:23]
	s_nop 0
	v_pk_mul_f32 v[22:23], v[18:19], v[16:17]
	v_cvt_pk_bf16_f32 v16, v28, v29
	v_cvt_pk_bf16_f32 v17, v20, v21
	v_cvt_pk_bf16_f32 v18, v24, v25
	v_cvt_pk_bf16_f32 v19, v22, v23
	global_store_dwordx4 v[10:11], v[16:19], off
	v_lshl_add_u64 v[10:11], v[10:11], 0, s[10:11]
	s_nop 1
	s_waitcnt vmcnt(4) lgkmcnt(1)
	v_mov_b32_e32 v16, v96
	v_mov_b32_e32 v17, v97
	v_mov_b32_e32 v18, v98
	v_mov_b32_e32 v19, v99
	v_mov_b32_e32 v20, v64
	v_mov_b32_e32 v21, v65
	v_mov_b32_e32 v22, v66
	v_mov_b32_e32 v23, v67
	v_mov_b32_e32 v24, v80
	v_mov_b32_e32 v25, v81
	v_mov_b32_e32 v26, v82
	v_mov_b32_e32 v27, v83
	v_and_b32_e32 v31, 0xffff0000, v16
	v_lshlrev_b32_e32 v30, 16, v16
	v_and_b32_e32 v29, 0xffff0000, v20
	v_lshlrev_b32_e32 v28, 16, v20
	v_lshlrev_b32_e32 v20, 16, v17
	v_and_b32_e32 v33, 0xffff0000, v24
	v_lshlrev_b32_e32 v32, 16, v24
	v_pk_fma_f32 v[30:31], v[6:7], v[32:33], v[30:31]
	v_lshlrev_b32_e32 v16, 16, v25
	v_pk_mul_f32 v[28:29], v[30:31], v[28:29]
	v_and_b32_e32 v31, 0xffff0000, v21
	v_lshlrev_b32_e32 v30, 16, v21
	v_and_b32_e32 v21, 0xffff0000, v17
	v_and_b32_e32 v17, 0xffff0000, v25
	v_pk_fma_f32 v[16:17], v[8:9], v[16:17], v[20:21]
	v_and_b32_e32 v25, 0xffff0000, v18
	v_pk_mul_f32 v[20:21], v[16:17], v[30:31]
	v_lshlrev_b32_e32 v24, 16, v18
	v_and_b32_e32 v31, 0xffff0000, v26
	v_lshlrev_b32_e32 v30, 16, v26
	v_and_b32_e32 v17, 0xffff0000, v22
	v_lshlrev_b32_e32 v16, 16, v22
	v_pk_fma_f32 v[24:25], v[2:3], v[30:31], v[24:25]
	v_lshlrev_b32_e32 v22, 16, v19
	v_pk_mul_f32 v[24:25], v[24:25], v[16:17]
	v_and_b32_e32 v17, 0xffff0000, v23
	v_lshlrev_b32_e32 v16, 16, v23
	v_and_b32_e32 v23, 0xffff0000, v19
	v_and_b32_e32 v19, 0xffff0000, v27
	v_lshlrev_b32_e32 v18, 16, v27
	v_pk_fma_f32 v[18:19], v[4:5], v[18:19], v[22:23]
	s_nop 0
	v_pk_mul_f32 v[22:23], v[18:19], v[16:17]
	v_cvt_pk_bf16_f32 v16, v28, v29
	v_cvt_pk_bf16_f32 v17, v20, v21
	v_cvt_pk_bf16_f32 v18, v24, v25
	v_cvt_pk_bf16_f32 v19, v22, v23
	global_store_dwordx4 v[10:11], v[16:19], off
	v_lshl_add_u64 v[10:11], v[10:11], 0, s[10:11]
	s_nop 1
	s_waitcnt vmcnt(3) lgkmcnt(0)
	v_mov_b32_e32 v16, v100
	v_mov_b32_e32 v17, v101
	v_mov_b32_e32 v18, v102
	v_mov_b32_e32 v19, v103
	v_mov_b32_e32 v20, v68
	v_mov_b32_e32 v21, v69
	v_mov_b32_e32 v22, v70
	v_mov_b32_e32 v23, v71
	v_mov_b32_e32 v24, v84
	v_mov_b32_e32 v25, v85
	v_mov_b32_e32 v26, v86
	v_mov_b32_e32 v27, v87
	v_and_b32_e32 v31, 0xffff0000, v16
	v_lshlrev_b32_e32 v30, 16, v16
	v_and_b32_e32 v29, 0xffff0000, v20
	v_lshlrev_b32_e32 v28, 16, v20
	v_lshlrev_b32_e32 v20, 16, v17
	v_and_b32_e32 v33, 0xffff0000, v24
	v_lshlrev_b32_e32 v32, 16, v24
	v_pk_fma_f32 v[30:31], v[6:7], v[32:33], v[30:31]
	v_lshlrev_b32_e32 v16, 16, v25
	v_pk_mul_f32 v[28:29], v[30:31], v[28:29]
	v_and_b32_e32 v31, 0xffff0000, v21
	v_lshlrev_b32_e32 v30, 16, v21
	v_and_b32_e32 v21, 0xffff0000, v17
	v_and_b32_e32 v17, 0xffff0000, v25
	v_pk_fma_f32 v[16:17], v[8:9], v[16:17], v[20:21]
	v_and_b32_e32 v25, 0xffff0000, v18
	v_pk_mul_f32 v[20:21], v[16:17], v[30:31]
	v_lshlrev_b32_e32 v24, 16, v18
	v_and_b32_e32 v31, 0xffff0000, v26
	v_lshlrev_b32_e32 v30, 16, v26
	v_and_b32_e32 v17, 0xffff0000, v22
	v_lshlrev_b32_e32 v16, 16, v22
	v_pk_fma_f32 v[24:25], v[2:3], v[30:31], v[24:25]
	v_lshlrev_b32_e32 v22, 16, v19
	v_pk_mul_f32 v[24:25], v[24:25], v[16:17]
	v_and_b32_e32 v17, 0xffff0000, v23
	v_lshlrev_b32_e32 v16, 16, v23
	v_and_b32_e32 v23, 0xffff0000, v19
	v_and_b32_e32 v19, 0xffff0000, v27
	v_lshlrev_b32_e32 v18, 16, v27
	v_pk_fma_f32 v[18:19], v[4:5], v[18:19], v[22:23]
	s_nop 0
	v_pk_mul_f32 v[22:23], v[18:19], v[16:17]
	v_cvt_pk_bf16_f32 v16, v28, v29
	v_cvt_pk_bf16_f32 v17, v20, v21
	v_cvt_pk_bf16_f32 v18, v24, v25
	v_cvt_pk_bf16_f32 v19, v22, v23
	global_store_dwordx4 v[10:11], v[16:19], off
	v_lshl_add_u64 v[10:11], v[10:11], 0, s[10:11]
	s_nop 1
	s_branch .LBB0_497

.LBB0_541:
	v_mov_b32_e32 v2, v202
	s_load_dwordx4 s[44:47], s[8:9], 0xb0
	s_mul_i32 s4, s58, 0x600
	v_add_u32_e32 v8, s4, v2
	v_ashrrev_i32_e32 v3, 31, v2
	v_readlane_b32 s4, v254, 55
	s_waitcnt lgkmcnt(0)
	v_mov_b32_e32 v4, s44
	v_mov_b32_e32 v5, s45
	v_lshl_add_u64 v[4:5], v[2:3], 2, v[4:5]
	v_readlane_b32 s5, v254, 56
	v_ashrrev_i32_e32 v9, 31, v8
	v_lshl_add_u64 v[42:43], v[8:9], 2, s[46:47]
	v_lshl_add_u64 v[6:7], v[4:5], 0, s[4:5]
	v_add_co_u32_e32 v4, vcc, 0x1000, v6
	global_load_dword v0, v[42:43], off
	s_nop 0
	v_addc_co_u32_e32 v5, vcc, 0, v7, vcc
	v_add_co_u32_e32 v10, vcc, 0x3000, v6
	s_lshl_b32 s44, s7, 4
	s_nop 0
	v_addc_co_u32_e32 v11, vcc, 0, v7, vcc
	global_load_dword v9, v[6:7], off
	global_load_dword v45, v[4:5], off offset:2048
	global_load_dword v44, v[10:11], off
	s_cmpk_lt_i32 s7, 0x100
	s_cselect_b64 s[14:15], -1, 0
	s_and_b64 s[10:11], s[14:15], exec
	s_movk_i32 s4, 0xf0
	s_cselect_b32 s4, s4, 0x3f0
	s_and_b32 s10, s4, s44
	s_cmp_lg_u32 s10, 0
	v_readlane_b32 s4, v254, 37
	s_cselect_b64 s[42:43], -1, 0
	s_add_i32 s82, s44, -1
	v_readlane_b32 s5, v254, 38
	s_cmp_eq_u32 s10, 0
	v_mov_b32_e32 v46, 0
	v_lshl_add_u64 v[4:5], v[2:3], 1, s[4:5]
	v_mov_b32_e32 v72, 0
	s_cbranch_scc1 .LBB0_543
	s_ashr_i32 s83, s82, 31
	s_lshl_b64 s[18:19], s[82:83], 12
	v_lshl_add_u64 v[10:11], v[4:5], 0, s[18:19]
	global_load_ushort v72, v[10:11], off

.LBB0_545:
	v_add_co_u32_e32 v54, vcc, 0x2000, v6
	global_load_dword v42, v[42:43], off offset:2048
	s_nop 0
	global_load_dword v43, v[6:7], off offset:2048
	v_addc_co_u32_e32 v55, vcc, 0, v7, vcc
	global_load_dword v47, v[54:55], off
	v_add_co_u32_e32 v54, vcc, 0x3000, v6
	v_cndmask_b32_e64 v53, 0, 1, s[42:43]
	s_nop 0
	v_addc_co_u32_e32 v55, vcc, 0, v7, vcc
	global_load_dword v49, v[54:55], off offset:2048
	v_mov_b32_e32 v50, 0
	v_cmp_ne_u32_e64 s[40:41], 1, v53
	s_andn2_b64 vcc, exec, s[42:43]
	v_mov_b32_e32 v83, 0
	s_cbranch_vccnz .LBB0_547
	s_ashr_i32 s83, s82, 31
	s_lshl_b64 s[4:5], s[82:83], 12
	v_lshl_add_u64 v[54:55], v[4:5], 0, s[4:5]
	global_load_ushort v83, v[54:55], off offset:1024

.LBB0_549:
	v_add_u32_e32 v54, 0x400, v8
	v_ashrrev_i32_e32 v55, 31, v54
	v_lshl_add_u64 v[54:55], v[54:55], 2, s[46:47]
	global_load_dword v8, v[54:55], off
	v_add_co_u32_e32 v54, vcc, 0x1000, v6
	s_movk_i32 s84, 0x104
	s_nop 0
	v_addc_co_u32_e32 v55, vcc, 0, v7, vcc
	v_add_co_u32_e32 v88, vcc, 0x2000, v6
	global_load_dword v54, v[54:55], off
	s_nop 0
	v_addc_co_u32_e32 v89, vcc, 0, v7, vcc
	v_add_co_u32_e32 v6, vcc, 0x4000, v6
	s_mov_b32 s86, 0x5040100
	s_nop 0
	v_addc_co_u32_e32 v7, vcc, 0, v7, vcc
	global_load_dword v6, v[6:7], off
	v_mov_b32_e32 v7, 0
	global_load_dword v55, v[88:89], off offset:2048
	s_and_b64 vcc, exec, s[40:41]
	v_mov_b32_e32 v89, 0
	s_cbranch_vccnz .LBB0_551
	s_ashr_i32 s83, s82, 31
	s_lshl_b64 s[4:5], s[82:83], 12
	v_lshl_add_u64 v[88:89], v[4:5], 0, s[4:5]
	global_load_ushort v89, v[88:89], off offset:2048
.LBB0_551:
	global_load_ushort v91, v[10:11], off offset:2048
	global_load_ushort v90, v[12:13], off offset:2048
	global_load_ushort v88, v[14:15], off offset:2048
	global_load_ushort v87, v[16:17], off offset:2048
	global_load_ushort v84, v[18:19], off offset:2048
	s_nop 0
	global_load_ushort v20, v[20:21], off offset:2048
	s_nop 0
	global_load_ushort v19, v[22:23], off offset:2048
	global_load_ushort v18, v[24:25], off offset:2048
	global_load_ushort v17, v[26:27], off offset:2048
	global_load_ushort v16, v[28:29], off offset:2048
	global_load_ushort v15, v[30:31], off offset:2048
	global_load_ushort v14, v[32:33], off offset:2048
	global_load_ushort v13, v[34:35], off offset:2048
	global_load_ushort v12, v[36:37], off offset:2048
	global_load_ushort v11, v[38:39], off offset:2048
	global_load_ushort v10, v[40:41], off offset:2048
	s_and_b64 vcc, exec, s[42:43]
	s_cbranch_vccnz .LBB0_553
	s_lshl_b64 s[4:5], s[44:45], 12
	v_lshl_add_u64 v[4:5], v[4:5], 0, s[4:5]
	v_add_co_u32_e32 v4, vcc, 0x10000, v4
	s_nop 1
	v_addc_co_u32_e32 v5, vcc, 0, v5, vcc
	global_load_ushort v7, v[4:5], off offset:2048
.LBB0_553:
	s_waitcnt vmcnt(0)
	v_lshlrev_b32_e32 v72, 16, v72
	v_lshlrev_b32_e32 v46, 16, v46
	v_lshlrev_b32_e32 v83, 16, v83
	v_lshlrev_b32_e32 v50, 16, v50
	v_lshlrev_b32_e32 v89, 16, v89
	v_lshlrev_b32_e32 v7, 16, v7
	v_lshlrev_b32_e32 v27, 16, v86
	v_lshlrev_b32_e32 v29, 16, v91
	v_mul_f32_e32 v22, v47, v27
	v_mul_f32_e32 v23, v55, v29
	v_fmac_f32_e32 v22, v43, v83
	v_lshlrev_b32_e32 v28, 16, v85
	v_fmac_f32_e32 v23, v54, v89
	v_lshlrev_b32_e32 v30, 16, v90
	v_lshlrev_b32_e32 v5, 16, v80
	v_fmac_f32_e32 v22, v49, v28
	v_fmac_f32_e32 v23, v6, v30
	v_mul_f32_e32 v21, v45, v5
	v_add_f32_e32 v22, v42, v22
	v_add_f32_e32 v23, v8, v23
	v_fmac_f32_e32 v21, v9, v72
	v_lshlrev_b32_e32 v26, 16, v79
	v_mul_f32_e32 v22, v22, v23
	v_fmac_f32_e32 v21, v44, v26
	v_bfe_u32 v23, v22, 16, 1
	v_add_f32_e32 v21, v0, v21
	v_add3_u32 v22, v22, v23, s27
	v_lshrrev_b32_e32 v31, 16, v22
	v_bfe_u32 v22, v21, 16, 1
	s_lshl_b64 s[4:5], s[44:45], 9
	v_add3_u32 v21, v21, v22, s27
	v_lshl_add_u64 v[22:23], s[4:5], 0, v[2:3]
	v_readlane_b32 s10, v254, 49
	v_lshlrev_b64 v[22:23], 1, v[22:23]
	v_readlane_b32 s11, v254, 50
	v_lshl_add_u32 v4, v2, 1, 0
	ds_write_b16 v4, v31
	v_lshl_add_u64 v[24:25], s[10:11], 0, v[22:23]
	v_lshl_add_u64 v[22:23], s[0:1], 0, v[22:23]
	global_store_short v[22:23], v31, off
	v_mul_f32_e32 v22, v47, v28
	v_mul_f32_e32 v23, v55, v30
	v_fmac_f32_e32 v22, v43, v27
	v_lshlrev_b32_e32 v27, 16, v82
	v_fmac_f32_e32 v23, v54, v29
	v_lshlrev_b32_e32 v29, 16, v88
	v_fmac_f32_e32 v22, v49, v27
	v_fmac_f32_e32 v23, v6, v29
	global_store_short_d16_hi v[24:25], v21, off
	v_mul_f32_e32 v21, v45, v26
	v_add_f32_e32 v22, v42, v22
	v_add_f32_e32 v23, v8, v23
	v_fmac_f32_e32 v21, v9, v5
	v_lshlrev_b32_e32 v5, 16, v77
	v_mul_f32_e32 v22, v22, v23
	v_fmac_f32_e32 v21, v44, v5
	v_bfe_u32 v23, v22, 16, 1
	v_add_f32_e32 v21, v0, v21
	v_add3_u32 v22, v22, v23, s27
	v_lshrrev_b32_e32 v31, 16, v22
	v_bfe_u32 v22, v21, 16, 1
	s_lshl_b64 s[4:5], s[76:77], 9
	v_add3_u32 v21, v21, v22, s27
	v_lshl_add_u64 v[22:23], s[4:5], 0, v[2:3]
	v_lshlrev_b64 v[22:23], 1, v[22:23]
	v_lshl_add_u64 v[24:25], s[10:11], 0, v[22:23]
	v_lshl_add_u64 v[22:23], s[0:1], 0, v[22:23]
	global_store_short v[22:23], v31, off
	v_mul_f32_e32 v22, v47, v27
	v_mul_f32_e32 v23, v55, v29
	v_fmac_f32_e32 v22, v43, v28
	v_lshlrev_b32_e32 v28, 16, v81
	v_fmac_f32_e32 v23, v54, v30
	v_lshlrev_b32_e32 v30, 16, v87
	v_fmac_f32_e32 v22, v49, v28
	v_fmac_f32_e32 v23, v6, v30
	global_store_short_d16_hi v[24:25], v21, off
	v_mul_f32_e32 v21, v45, v5
	v_add_f32_e32 v22, v42, v22
	v_add_f32_e32 v23, v8, v23
	v_fmac_f32_e32 v21, v9, v26
	v_lshlrev_b32_e32 v26, 16, v75
	v_mul_f32_e32 v22, v22, v23
	v_fmac_f32_e32 v21, v44, v26
	v_bfe_u32 v23, v22, 16, 1
	v_add_f32_e32 v21, v0, v21
	v_add3_u32 v22, v22, v23, s27
	ds_write_b16 v4, v31 offset:1040
	v_lshrrev_b32_e32 v31, 16, v22
	v_bfe_u32 v22, v21, 16, 1
	s_lshl_b64 s[4:5], s[74:75], 9
	v_add3_u32 v21, v21, v22, s27
	v_lshl_add_u64 v[22:23], s[4:5], 0, v[2:3]
	v_lshlrev_b64 v[22:23], 1, v[22:23]
	v_lshl_add_u64 v[24:25], s[10:11], 0, v[22:23]
	v_lshl_add_u64 v[22:23], s[0:1], 0, v[22:23]
	global_store_short v[22:23], v31, off
	v_mul_f32_e32 v22, v47, v28
	v_mul_f32_e32 v23, v55, v30
	v_fmac_f32_e32 v22, v43, v27
	v_lshlrev_b32_e32 v27, 16, v78
	v_fmac_f32_e32 v23, v54, v29
	v_lshlrev_b32_e32 v29, 16, v84
	v_fmac_f32_e32 v22, v49, v27
	v_fmac_f32_e32 v23, v6, v29
	global_store_short_d16_hi v[24:25], v21, off
	v_mul_f32_e32 v21, v45, v26
	v_add_f32_e32 v22, v42, v22
	v_add_f32_e32 v23, v8, v23
	v_fmac_f32_e32 v21, v9, v5
	v_lshlrev_b32_e32 v5, 16, v73
	v_mul_f32_e32 v22, v22, v23
	v_fmac_f32_e32 v21, v44, v5
	v_bfe_u32 v23, v22, 16, 1
	v_add_f32_e32 v21, v0, v21
	v_add3_u32 v22, v22, v23, s27
	ds_write_b16 v4, v31 offset:2080
	v_lshrrev_b32_e32 v31, 16, v22
	v_bfe_u32 v22, v21, 16, 1
	s_lshl_b64 s[4:5], s[72:73], 9
	v_add3_u32 v21, v21, v22, s27
	v_lshl_add_u64 v[22:23], s[4:5], 0, v[2:3]
	v_lshlrev_b64 v[22:23], 1, v[22:23]
	v_lshl_add_u64 v[24:25], s[10:11], 0, v[22:23]
	v_lshl_add_u64 v[22:23], s[0:1], 0, v[22:23]
	global_store_short_d16_hi v[24:25], v21, off
	global_store_short v[22:23], v31, off
	v_mul_f32_e32 v21, v45, v5
	v_mul_f32_e32 v22, v47, v27
	v_mul_f32_e32 v23, v55, v29
	v_fmac_f32_e32 v21, v9, v26
	v_fmac_f32_e32 v22, v43, v28
	v_lshlrev_b32_e32 v25, 16, v76
	v_fmac_f32_e32 v23, v54, v30
	v_lshlrev_b32_e32 v26, 16, v20
	v_fmac_f32_e32 v22, v49, v25
	v_fmac_f32_e32 v23, v6, v26
	v_add_f32_e32 v22, v42, v22
	v_add_f32_e32 v20, v8, v23
	v_lshlrev_b32_e32 v24, 16, v70
	v_mul_f32_e32 v20, v22, v20
	v_fmac_f32_e32 v21, v44, v24
	v_bfe_u32 v22, v20, 16, 1
	v_add_f32_e32 v21, v0, v21
	v_add3_u32 v20, v20, v22, s27
	v_lshrrev_b32_e32 v28, 16, v20
	v_bfe_u32 v20, v21, 16, 1
	s_lshl_b64 s[4:5], s[70:71], 9
	v_add3_u32 v30, v21, v20, s27
	v_lshl_add_u64 v[20:21], s[4:5], 0, v[2:3]
	v_lshlrev_b64 v[20:21], 1, v[20:21]
	v_lshl_add_u64 v[22:23], s[10:11], 0, v[20:21]
	v_lshl_add_u64 v[20:21], s[0:1], 0, v[20:21]
	global_store_short_d16_hi v[22:23], v30, off
	global_store_short v[20:21], v28, off
	v_mul_f32_e32 v21, v47, v25
	v_mul_f32_e32 v22, v55, v26
	ds_write_b16 v4, v28 offset:4160
	v_fmac_f32_e32 v21, v43, v27
	v_lshlrev_b32_e32 v27, 16, v74
	v_fmac_f32_e32 v22, v54, v29
	v_lshlrev_b32_e32 v28, 16, v19
	v_mul_f32_e32 v20, v45, v24
	v_fmac_f32_e32 v21, v49, v27
	v_fmac_f32_e32 v22, v6, v28
	v_fmac_f32_e32 v20, v9, v5
	v_lshlrev_b32_e32 v5, 16, v68
	v_add_f32_e32 v21, v42, v21
	v_add_f32_e32 v19, v8, v22
	v_fmac_f32_e32 v20, v44, v5
	v_mul_f32_e32 v19, v21, v19
	v_add_f32_e32 v20, v0, v20
	v_bfe_u32 v21, v19, 16, 1
	v_add3_u32 v19, v19, v21, s27
	v_bfe_u32 v21, v20, 16, 1
	s_lshl_b64 s[4:5], s[68:69], 9
	v_add3_u32 v29, v20, v21, s27
	v_lshl_add_u64 v[20:21], s[4:5], 0, v[2:3]
	v_lshlrev_b64 v[20:21], 1, v[20:21]
	v_lshrrev_b32_e32 v19, 16, v19
	v_lshl_add_u64 v[22:23], s[10:11], 0, v[20:21]
	v_lshl_add_u64 v[20:21], s[0:1], 0, v[20:21]
	global_store_short v[20:21], v19, off
	ds_write_b16 v4, v19 offset:5200
	v_mul_f32_e32 v19, v45, v5
	v_mul_f32_e32 v20, v47, v27
	v_mul_f32_e32 v21, v55, v28
	global_store_short_d16_hi v[22:23], v29, off
	v_fmac_f32_e32 v19, v9, v24
	v_fmac_f32_e32 v20, v43, v25
	v_lshlrev_b32_e32 v23, 16, v71
	v_fmac_f32_e32 v21, v54, v26
	v_lshlrev_b32_e32 v24, 16, v18
	v_fmac_f32_e32 v20, v49, v23
	v_fmac_f32_e32 v21, v6, v24
	v_add_f32_e32 v20, v42, v20
	v_add_f32_e32 v18, v8, v21
	v_lshlrev_b32_e32 v22, 16, v66
	v_mul_f32_e32 v18, v20, v18
	v_fmac_f32_e32 v19, v44, v22
	v_bfe_u32 v20, v18, 16, 1
	v_add_f32_e32 v19, v0, v19
	v_add3_u32 v18, v18, v20, s27
	v_lshrrev_b32_e32 v25, 16, v18
	v_bfe_u32 v18, v19, 16, 1
	s_lshl_b64 s[4:5], s[66:67], 9
	v_add3_u32 v26, v19, v18, s27
	v_lshl_add_u64 v[18:19], s[4:5], 0, v[2:3]
	v_lshlrev_b64 v[18:19], 1, v[18:19]
	v_lshl_add_u64 v[20:21], s[10:11], 0, v[18:19]
	v_lshl_add_u64 v[18:19], s[0:1], 0, v[18:19]
	global_store_short_d16_hi v[20:21], v26, off
	global_store_short v[18:19], v25, off
	v_mul_f32_e32 v19, v47, v23
	v_mul_f32_e32 v20, v55, v24
	ds_write_b16 v4, v25 offset:6240
	v_fmac_f32_e32 v19, v43, v27
	v_lshlrev_b32_e32 v25, 16, v69
	v_fmac_f32_e32 v20, v54, v28
	v_lshlrev_b32_e32 v26, 16, v17
	v_mul_f32_e32 v18, v45, v22
	v_fmac_f32_e32 v19, v49, v25
	v_fmac_f32_e32 v20, v6, v26
	v_fmac_f32_e32 v18, v9, v5
	v_lshlrev_b32_e32 v5, 16, v64
	v_add_f32_e32 v19, v42, v19
	v_add_f32_e32 v17, v8, v20
	v_fmac_f32_e32 v18, v44, v5
	v_mul_f32_e32 v17, v19, v17
	v_add_f32_e32 v18, v0, v18
	v_bfe_u32 v19, v17, 16, 1
	v_add3_u32 v17, v17, v19, s27
	v_bfe_u32 v19, v18, 16, 1
	s_lshl_b64 s[4:5], s[64:65], 9
	v_add3_u32 v27, v18, v19, s27
	v_lshl_add_u64 v[18:19], s[4:5], 0, v[2:3]
	v_lshlrev_b64 v[18:19], 1, v[18:19]
	v_lshrrev_b32_e32 v17, 16, v17
	v_lshl_add_u64 v[20:21], s[10:11], 0, v[18:19]
	v_lshl_add_u64 v[18:19], s[0:1], 0, v[18:19]
	global_store_short v[18:19], v17, off
	ds_write_b16 v4, v17 offset:7280
	v_mul_f32_e32 v17, v45, v5
	v_mul_f32_e32 v18, v47, v25
	v_mul_f32_e32 v19, v55, v26
	global_store_short_d16_hi v[20:21], v27, off
	v_fmac_f32_e32 v17, v9, v22
	v_fmac_f32_e32 v18, v43, v23
	v_lshlrev_b32_e32 v21, 16, v67
	v_fmac_f32_e32 v19, v54, v24
	v_lshlrev_b32_e32 v22, 16, v16
	v_fmac_f32_e32 v18, v49, v21
	v_fmac_f32_e32 v19, v6, v22
	v_add_f32_e32 v18, v42, v18
	v_add_f32_e32 v16, v8, v19
	v_lshlrev_b32_e32 v20, 16, v62
	v_mul_f32_e32 v16, v18, v16
	v_fmac_f32_e32 v17, v44, v20
	v_bfe_u32 v18, v16, 16, 1
	v_add_f32_e32 v17, v0, v17
	v_add3_u32 v16, v16, v18, s27
	v_lshrrev_b32_e32 v23, 16, v16
	v_bfe_u32 v16, v17, 16, 1
	s_lshl_b64 s[4:5], s[62:63], 9
	v_add3_u32 v24, v17, v16, s27
	v_lshl_add_u64 v[16:17], s[4:5], 0, v[2:3]
	v_lshlrev_b64 v[16:17], 1, v[16:17]
	v_lshl_add_u64 v[18:19], s[10:11], 0, v[16:17]
	v_lshl_add_u64 v[16:17], s[0:1], 0, v[16:17]
	global_store_short_d16_hi v[18:19], v24, off
	global_store_short v[16:17], v23, off
	v_mul_f32_e32 v17, v47, v21
	v_mul_f32_e32 v18, v55, v22
	ds_write_b16 v4, v23 offset:8320
	v_fmac_f32_e32 v17, v43, v25
	v_lshlrev_b32_e32 v23, 16, v65
	v_fmac_f32_e32 v18, v54, v26
	v_lshlrev_b32_e32 v24, 16, v15
	v_mul_f32_e32 v16, v45, v20
	v_fmac_f32_e32 v17, v49, v23
	v_fmac_f32_e32 v18, v6, v24
	v_fmac_f32_e32 v16, v9, v5
	v_lshlrev_b32_e32 v5, 16, v60
	v_add_f32_e32 v17, v42, v17
	v_add_f32_e32 v15, v8, v18
	v_fmac_f32_e32 v16, v44, v5
	v_mul_f32_e32 v15, v17, v15
	v_add_f32_e32 v16, v0, v16
	v_bfe_u32 v17, v15, 16, 1
	v_add3_u32 v15, v15, v17, s27
	v_bfe_u32 v17, v16, 16, 1
	s_lshl_b64 s[4:5], s[60:61], 9
	v_add3_u32 v25, v16, v17, s27
	v_lshl_add_u64 v[16:17], s[4:5], 0, v[2:3]
	v_lshlrev_b64 v[16:17], 1, v[16:17]
	v_lshrrev_b32_e32 v15, 16, v15
	v_lshl_add_u64 v[18:19], s[10:11], 0, v[16:17]
	v_lshl_add_u64 v[16:17], s[0:1], 0, v[16:17]
	global_store_short v[16:17], v15, off
	ds_write_b16 v4, v15 offset:9360
	v_mul_f32_e32 v15, v45, v5
	v_mul_f32_e32 v16, v47, v23
	v_mul_f32_e32 v17, v55, v24
	global_store_short_d16_hi v[18:19], v25, off
	v_fmac_f32_e32 v15, v9, v20
	v_fmac_f32_e32 v16, v43, v21
	v_lshlrev_b32_e32 v19, 16, v63
	v_fmac_f32_e32 v17, v54, v22
	v_lshlrev_b32_e32 v20, 16, v14
	v_fmac_f32_e32 v16, v49, v19
	v_fmac_f32_e32 v17, v6, v20
	v_add_f32_e32 v16, v42, v16
	v_add_f32_e32 v14, v8, v17
	v_lshlrev_b32_e32 v18, 16, v58
	v_mul_f32_e32 v14, v16, v14
	v_fmac_f32_e32 v15, v44, v18
	v_bfe_u32 v16, v14, 16, 1
	v_add_f32_e32 v15, v0, v15
	v_add3_u32 v14, v14, v16, s27
	v_lshrrev_b32_e32 v21, 16, v14
	v_bfe_u32 v14, v15, 16, 1
	s_lshl_b64 s[4:5], s[58:59], 9
	v_add3_u32 v22, v15, v14, s27
	v_lshl_add_u64 v[14:15], s[4:5], 0, v[2:3]
	v_lshlrev_b64 v[14:15], 1, v[14:15]
	v_lshl_add_u64 v[16:17], s[10:11], 0, v[14:15]
	v_lshl_add_u64 v[14:15], s[0:1], 0, v[14:15]
	global_store_short_d16_hi v[16:17], v22, off
	global_store_short v[14:15], v21, off
	v_mul_f32_e32 v15, v47, v19
	v_mul_f32_e32 v16, v55, v20
	ds_write_b16 v4, v21 offset:10400
	v_fmac_f32_e32 v15, v43, v23
	v_lshlrev_b32_e32 v21, 16, v61
	v_fmac_f32_e32 v16, v54, v24
	v_lshlrev_b32_e32 v22, 16, v13
	v_mul_f32_e32 v14, v45, v18
	v_fmac_f32_e32 v15, v49, v21
	v_fmac_f32_e32 v16, v6, v22
	v_fmac_f32_e32 v14, v9, v5
	v_lshlrev_b32_e32 v5, 16, v56
	v_add_f32_e32 v15, v42, v15
	v_add_f32_e32 v13, v8, v16
	v_fmac_f32_e32 v14, v44, v5
	v_mul_f32_e32 v13, v15, v13
	v_add_f32_e32 v14, v0, v14
	v_bfe_u32 v15, v13, 16, 1
	v_add3_u32 v13, v13, v15, s27
	v_bfe_u32 v15, v14, 16, 1
	s_lshl_b64 s[4:5], s[56:57], 9
	v_add3_u32 v23, v14, v15, s27
	v_lshl_add_u64 v[14:15], s[4:5], 0, v[2:3]
	v_lshlrev_b64 v[14:15], 1, v[14:15]
	v_lshrrev_b32_e32 v13, 16, v13
	v_lshl_add_u64 v[16:17], s[10:11], 0, v[14:15]
	v_lshl_add_u64 v[14:15], s[0:1], 0, v[14:15]
	global_store_short v[14:15], v13, off
	ds_write_b16 v4, v13 offset:11440
	v_mul_f32_e32 v13, v45, v5
	v_mul_f32_e32 v14, v47, v21
	v_mul_f32_e32 v15, v55, v22
	global_store_short_d16_hi v[16:17], v23, off
	v_fmac_f32_e32 v13, v9, v18
	v_fmac_f32_e32 v14, v43, v19
	v_lshlrev_b32_e32 v17, 16, v59
	v_fmac_f32_e32 v15, v54, v20
	v_lshlrev_b32_e32 v18, 16, v12
	v_fmac_f32_e32 v14, v49, v17
	v_fmac_f32_e32 v15, v6, v18
	v_add_f32_e32 v14, v42, v14
	v_add_f32_e32 v12, v8, v15
	v_lshlrev_b32_e32 v16, 16, v52
	v_mul_f32_e32 v12, v14, v12
	v_fmac_f32_e32 v13, v44, v16
	v_bfe_u32 v14, v12, 16, 1
	v_add_f32_e32 v13, v0, v13
	v_add3_u32 v12, v12, v14, s27
	v_lshrrev_b32_e32 v19, 16, v12
	v_bfe_u32 v12, v13, 16, 1
	s_lshl_b64 s[4:5], s[54:55], 9
	v_add3_u32 v20, v13, v12, s27
	v_lshl_add_u64 v[12:13], s[4:5], 0, v[2:3]
	v_lshlrev_b64 v[12:13], 1, v[12:13]
	v_lshl_add_u64 v[14:15], s[10:11], 0, v[12:13]
	v_lshl_add_u64 v[12:13], s[0:1], 0, v[12:13]
	global_store_short_d16_hi v[14:15], v20, off
	global_store_short v[12:13], v19, off
	v_mul_f32_e32 v13, v47, v17
	v_mul_f32_e32 v14, v55, v18
	ds_write_b16 v4, v19 offset:12480
	v_fmac_f32_e32 v13, v43, v21
	v_lshlrev_b32_e32 v19, 16, v57
	v_fmac_f32_e32 v14, v54, v22
	v_lshlrev_b32_e32 v20, 16, v11
	v_mul_f32_e32 v12, v45, v16
	v_fmac_f32_e32 v13, v49, v19
	v_fmac_f32_e32 v14, v6, v20
	v_fmac_f32_e32 v12, v9, v5
	v_lshlrev_b32_e32 v5, 16, v51
	v_add_f32_e32 v13, v42, v13
	v_add_f32_e32 v11, v8, v14
	v_fmac_f32_e32 v12, v44, v5
	v_mul_f32_e32 v11, v13, v11
	v_add_f32_e32 v12, v0, v12
	v_bfe_u32 v13, v11, 16, 1
	v_add3_u32 v11, v11, v13, s27
	v_bfe_u32 v13, v12, 16, 1
	s_lshl_b64 s[4:5], s[52:53], 9
	v_add3_u32 v21, v12, v13, s27
	v_lshl_add_u64 v[12:13], s[4:5], 0, v[2:3]
	v_lshlrev_b64 v[12:13], 1, v[12:13]
	v_lshrrev_b32_e32 v11, 16, v11
	v_lshl_add_u64 v[14:15], s[10:11], 0, v[12:13]
	v_lshl_add_u64 v[12:13], s[0:1], 0, v[12:13]
	global_store_short v[12:13], v11, off
	ds_write_b16 v4, v11 offset:13520
	v_mul_f32_e32 v11, v45, v5
	v_mul_f32_e32 v12, v47, v19
	v_mul_f32_e32 v13, v55, v20
	global_store_short_d16_hi v[14:15], v21, off
	v_fmac_f32_e32 v11, v9, v16
	v_fmac_f32_e32 v12, v43, v17
	v_lshlrev_b32_e32 v15, 16, v53
	v_fmac_f32_e32 v13, v54, v18
	v_lshlrev_b32_e32 v16, 16, v10
	v_fmac_f32_e32 v12, v49, v15
	v_fmac_f32_e32 v13, v6, v16
	v_add_f32_e32 v12, v42, v12
	v_add_f32_e32 v10, v8, v13
	v_lshlrev_b32_e32 v14, 16, v48
	v_mul_f32_e32 v10, v12, v10
	v_fmac_f32_e32 v11, v44, v14
	v_bfe_u32 v12, v10, 16, 1
	v_add_f32_e32 v11, v0, v11
	v_add3_u32 v10, v10, v12, s27
	v_lshrrev_b32_e32 v17, 16, v10
	v_bfe_u32 v10, v11, 16, 1
	s_lshl_b64 s[4:5], s[50:51], 9
	v_add3_u32 v18, v11, v10, s27
	v_lshl_add_u64 v[10:11], s[4:5], 0, v[2:3]
	v_lshlrev_b64 v[10:11], 1, v[10:11]
	v_lshl_add_u64 v[12:13], s[10:11], 0, v[10:11]
	v_lshl_add_u64 v[10:11], s[0:1], 0, v[10:11]
	global_store_short v[10:11], v17, off
	v_mul_f32_e32 v10, v45, v14
	v_fmac_f32_e32 v10, v9, v5
	v_mul_f32_e32 v5, v47, v15
	v_mul_f32_e32 v9, v55, v16
	v_fmac_f32_e32 v5, v43, v19
	v_fmac_f32_e32 v9, v54, v20
	v_fmac_f32_e32 v5, v49, v50
	v_fmac_f32_e32 v9, v6, v7
	v_add_f32_e32 v5, v42, v5
	v_add_f32_e32 v6, v8, v9
	v_fmac_f32_e32 v10, v44, v46
	v_mul_f32_e32 v5, v5, v6
	v_add_f32_e32 v0, v0, v10
	v_bfe_u32 v6, v5, 16, 1
	v_add3_u32 v5, v5, v6, s27
	v_bfe_u32 v6, v0, 16, 1
	s_lshl_b64 s[4:5], s[48:49], 9
	v_add3_u32 v0, v0, v6, s27
	v_lshl_add_u64 v[6:7], s[4:5], 0, v[2:3]
	v_lshlrev_b64 v[6:7], 1, v[6:7]
	v_lshrrev_b32_e32 v5, 16, v5
	v_lshl_add_u64 v[8:9], s[10:11], 0, v[6:7]
	v_lshl_add_u64 v[6:7], s[0:1], 0, v[6:7]
	ds_write_b16 v4, v31 offset:3120
	global_store_short_d16_hi v[12:13], v18, off
	ds_write_b16 v4, v17 offset:14560
	global_store_short_d16_hi v[8:9], v0, off
	global_store_short v[6:7], v5, off
	ds_write_b16 v4, v5 offset:15600
	s_waitcnt lgkmcnt(0)
	s_barrier
	ds_read_u16 v0, v4
	ds_read_u16 v3, v4 offset:1040
	ds_read_u16 v5, v4 offset:2080
	ds_read_u16 v8, v4 offset:3120
	ds_read_u16 v9, v4 offset:4160
	ds_read_u16 v12, v4 offset:5200
	ds_read_u16 v13, v4 offset:6240
	ds_read_u16 v14, v4 offset:7280
	v_readlane_b32 s4, v254, 47
	v_readlane_b32 s5, v254, 48
	s_movk_i32 s68, 0x3000
	v_ashrrev_i32_e32 v24, 6, v2
	v_mov_b64_e32 v[6:7], s[4:5]
	v_mad_i64_i32 v[6:7], s[4:5], v2, s68, v[6:7]
	v_lshl_add_u64 v[10:11], s[44:45], 1, v[6:7]
	s_waitcnt lgkmcnt(6)
	v_lshl_or_b32 v6, v3, 16, v0
	s_waitcnt lgkmcnt(4)
	v_lshl_or_b32 v7, v8, 16, v5
	s_waitcnt lgkmcnt(2)
	v_lshl_or_b32 v8, v12, 16, v9
	s_waitcnt lgkmcnt(0)
	v_lshl_or_b32 v9, v14, 16, v13
	ds_read_u16 v0, v4 offset:8320
	ds_read_u16 v3, v4 offset:9360
	ds_read_u16 v5, v4 offset:10400
	ds_read_u16 v12, v4 offset:11440
	ds_read_u16 v13, v4 offset:12480
	ds_read_u16 v14, v4 offset:13520
	ds_read_u16 v15, v4 offset:14560
	ds_read_u16 v16, v4 offset:15600
	global_store_dwordx4 v[10:11], v[6:9], off
	s_waitcnt lgkmcnt(6)
	v_lshl_or_b32 v4, v3, 16, v0
	s_waitcnt lgkmcnt(4)
	v_lshl_or_b32 v5, v12, 16, v5
	s_waitcnt lgkmcnt(2)
	v_lshl_or_b32 v6, v14, 16, v13
	s_waitcnt lgkmcnt(0)
	v_lshl_or_b32 v7, v16, 16, v15
	v_cmp_gt_i32_e32 vcc, 16, v24
	global_store_dwordx4 v[10:11], v[4:7], off offset:16
	s_and_saveexec_b64 s[46:47], vcc
	v_readlane_b32 s70, v254, 34
	v_readlane_b32 s58, v254, 44
	v_readlane_b32 s56, v254, 32
	s_mov_b32 s57, 0xe0000
	v_readlane_b32 s69, v253, 27
	s_mov_b64 s[16:17], 0x1000
	s_mov_b64 s[18:19], 0x8000
	v_readlane_b32 s71, v254, 35
	v_readlane_b32 s72, v254, 36
	v_readlane_b32 s59, v254, 45
	s_cbranch_execz .LBB0_540
	v_and_b32_e32 v3, 64, v210
	v_add_u32_e32 v3, 64, v3
	v_xor_b32_e32 v4, 32, v210
	v_cmp_lt_i32_e32 vcc, v4, v3
	s_load_dwordx2 s[4:5], s[8:9], 0xf8
	v_readlane_b32 s10, v254, 41
	v_cndmask_b32_e32 v4, v210, v4, vcc
	v_lshlrev_b32_e32 v25, 2, v4
	v_xor_b32_e32 v4, 16, v210
	v_cmp_lt_i32_e32 vcc, v4, v3
	v_readlane_b32 s11, v254, 42
	s_lshl_b64 s[10:11], s[10:11], 2
	v_cndmask_b32_e32 v4, v210, v4, vcc
	v_lshlrev_b32_e32 v26, 2, v4
	v_xor_b32_e32 v4, 8, v210
	v_cmp_lt_i32_e32 vcc, v4, v3
	v_and_b32_e32 v20, 63, v2
	s_waitcnt lgkmcnt(0)
	s_add_u32 s4, s4, s10
	v_cndmask_b32_e32 v4, v210, v4, vcc
	v_lshlrev_b32_e32 v27, 2, v4
	v_xor_b32_e32 v4, 4, v210
	v_cmp_lt_i32_e32 vcc, v4, v3
	s_addc_u32 s5, s5, s11
	v_mov_b32_e32 v5, v1
	v_cndmask_b32_e32 v4, v210, v4, vcc
	v_lshlrev_b32_e32 v28, 2, v4
	v_xor_b32_e32 v4, 2, v210
	v_cmp_lt_i32_e32 vcc, v4, v3
	v_lshlrev_b32_e32 v18, 1, v20
	v_add_u32_e32 v12, s3, v24
	v_cndmask_b32_e32 v4, v210, v4, vcc
	v_lshlrev_b32_e32 v29, 2, v4
	v_xor_b32_e32 v4, 1, v210
	v_cmp_lt_i32_e32 vcc, v4, v3
	v_ashrrev_i32_e32 v13, 31, v12
	s_load_dwordx2 s[12:13], s[8:9], 0x108
	s_load_dwordx2 s[48:49], s[8:9], 0x138
	v_cndmask_b32_e32 v3, v210, v4, vcc
	v_lshlrev_b32_e32 v30, 2, v3
	v_lshlrev_b32_e32 v4, 4, v20
	v_and_b32_e32 v3, 15, v2
	v_lshl_add_u64 v[4:5], s[4:5], 0, v[4:5]
	v_readlane_b32 s4, v254, 43
	v_cvt_f32_ubyte0_e32 v3, v3
	v_mul_f32_e32 v8, 0xbf549a78, v3
	v_or_b32_e32 v6, s4, v18
	s_mov_b32 s4, 0xc2fc0000
	v_cmp_gt_f32_e32 vcc, s4, v8
	v_and_b32_e32 v2, 16, v2
	v_readlane_b32 s4, v254, 57
	v_cndmask_b32_e32 v8, 0, v209, vcc
	v_fmac_f32_e32 v8, 0xbf549a78, v3
	v_exp_f32_e32 v3, v8
	v_cndmask_b32_e32 v8, 0, v208, vcc
	v_cmp_eq_u32_e64 s[40:41], 0, v2
	v_readlane_b32 s5, v254, 58
	v_ldexp_f32 v31, v3, v8
	v_lshlrev_b64 v[2:3], 7, v[12:13]
	v_mov_b32_e32 v19, v1
	v_lshl_add_u64 v[2:3], s[4:5], 0, v[2:3]
	v_readlane_b32 s4, v254, 62
	v_lshl_add_u64 v[2:3], v[2:3], 0, v[18:19]
	v_lshlrev_b64 v[10:11], 9, v[12:13]
	v_readlane_b32 s5, v254, 63
	v_lshlrev_b32_e32 v19, 3, v20
	v_lshlrev_b32_e32 v32, 6, v12
	v_lshlrev_b32_e32 v33, 7, v12
	v_lshl_add_u64 v[8:9], s[4:5], 0, v[10:11]
	v_or_b32_e32 v10, v10, v19
	s_mov_b64 s[4:5], 0x10a18000
	v_lshlrev_b64 v[12:13], 12, v[12:13]
	v_lshlrev_b32_e32 v0, 2, v20
	v_lshl_add_u64 v[10:11], v[10:11], 0, s[4:5]
	v_or_b32_e32 v14, v12, v18
	v_mov_b32_e32 v15, v13
	s_mov_b64 s[4:5], 0x2448f00
	v_mov_b32_e32 v7, v1
	s_waitcnt lgkmcnt(0)
	s_add_u32 s50, s48, 0x3000000
	v_lshl_add_u64 v[14:15], v[14:15], 0, s[4:5]
	v_or_b32_e32 v16, v12, v0
	v_mov_b32_e32 v17, v13
	s_mov_b64 s[4:5], 0x2448e00
	v_lshl_add_u64 v[6:7], v[6:7], 2, s[12:13]
	s_addc_u32 s51, s49, 0
	v_cmp_gt_u32_e64 s[42:43], 32, v20
	v_lshl_add_u64 v[8:9], v[8:9], 0, v[0:1]
	v_lshl_add_u64 v[16:17], v[16:17], 0, s[4:5]
	v_or_b32_e32 v12, v12, v19
	s_mov_b64 s[52:53], 0
	v_lshlrev_b32_e32 v18, 2, v18
	v_lshlrev_b32_e32 v20, 2, v20
	s_branch .LBB0_556
